# attention key loop shifted +8 bytes (placement scan)
# baseline (speedup 1.0000x reference)
; #define LAS __attribute__((address_space(3)))
; #define DMAT(kt, so) do { const unsigned rb_ = (unsigned)ROWBASE(kt); _Pragma("unroll") for (int r = 0; r < 3; ++r) if (wid + 8 * r < 22) \
;         __builtin_amdgcn_global_load_lds((const unsigned*)(dsrc[r] + (size_t)rb_ * dmul[r]), (LAS unsigned*)(lds + (so) + dlds[r]), 16, 0, 0); } while (0)
; __device__ __forceinline__ void attn_unit2(LAS unsigned char* lds, const bf16_t* __restrict__ Q, const bf16_t* __restrict__ KN, const bf16_t* __restrict__ KPE, ...
;     ...
;     f32x16 oa0 = {}, oa1 = {}, ob0 = {}, ob1 = {};
;     float ma = -1.0e30f, mb = -1.0e30f, la = 0.f, lb = 0.f;
;     for (int t = 0; t < ntiles; ++t) {
;         __builtin_amdgcn_sched_barrier(0);
;         f32x16 sa0 = {}, sa1 = {}, sb0 = {}, sb1 = {};
;         const LAS unsigned char* ka = lds + sc + ka_off;
; #pragma unroll
;         for (int ds = 0; ds < 6; ++ds) {
;             const bf16x8 k0 = *(const LAS bf16x8*)(ka + ds * 32);
;             const bf16x8 k1 = *(const LAS bf16x8*)(ka + 32 * KROW + ds * 32);
;             sa0 = __builtin_amdgcn_mfma_f32_32x32x16_bf16(k0, qa[ds], sa0, 0, 0, 0);
;             sa1 = __builtin_amdgcn_mfma_f32_32x32x16_bf16(k1, qa[ds], sa1, 0, 0, 0);
;             sb0 = __builtin_amdgcn_mfma_f32_32x32x16_bf16(k0, qb[ds], sb0, 0, 0, 0);
;             sb1 = __builtin_amdgcn_mfma_f32_32x32x16_bf16(k1, qb[ds], sb1, 0, 0, 0);
;         }
;         __builtin_amdgcn_sched_barrier(0);
;         if (t + 2 < ntiles) DMAT(t + 2, snn);
;         u32x4 pa[4], pb[4];
;     ...
;         for (int st = 0; st < 4; ++st) {
;             const bf16x8 v0 = *(const LAS bf16x8*)(va + st * 32);
;             const bf16x8 v1 = *(const LAS bf16x8*)(va + 32 * VROW + st * 32);
;             const bf16x8 fa = __builtin_bit_cast(bf16x8, pa[st]), fb = __builtin_bit_cast(bf16x8, pb[st]);
;             oa0 = __builtin_amdgcn_mfma_f32_32x32x16_bf16(v0, fa, oa0, 0, 0, 0);
;             oa1 = __builtin_amdgcn_mfma_f32_32x32x16_bf16(v1, fa, oa1, 0, 0, 0);
;             ob0 = __builtin_amdgcn_mfma_f32_32x32x16_bf16(v0, fb, ob0, 0, 0, 0);
;             ob1 = __builtin_amdgcn_mfma_f32_32x32x16_bf16(v1, fb, ob1, 0, 0, 0);
.Lat_noprio:
	v_mov_b32_e32 v96, 0
	v_mov_b32_e32 v97, 0
	v_mov_b32_e32 v98, 0
	v_mov_b32_e32 v99, 0
	v_mov_b32_e32 v100, 0
	v_mov_b32_e32 v101, 0
	v_mov_b32_e32 v102, 0
	v_mov_b32_e32 v103, 0
	v_mov_b32_e32 v112, 0
	v_mov_b32_e32 v113, 0
	v_mov_b32_e32 v114, 0
	v_mov_b32_e32 v115, 0
	v_mov_b32_e32 v116, 0
	v_mov_b32_e32 v117, 0
	v_mov_b32_e32 v118, 0
	v_mov_b32_e32 v119, 0
	v_sub_u32_e32 v228, 1, v192
	v_mul_u32_u24_e32 v228, 0xffff, v228
	v_and_b32_e32 v240, 0x3f80, v228
	v_mov_b32_e32 v241, 0
	v_mov_b32_e32 v242, 0
	v_mov_b32_e32 v243, 0
	v_and_b32_e32 v244, 0x4480, v228
	v_mov_b32_e32 v245, 0
	v_mov_b32_e32 v246, 0
	v_mov_b32_e32 v247, 0
	v_mov_b32_e32 v194, 0xc4800000
	v_and_b32_e32 v248, 0x4480, v228
	v_mov_b32_e32 v249, 0
	v_mov_b32_e32 v250, 0
	v_mov_b32_e32 v251, 0
	v_mov_b32_e32 v195, 0xc4800000
	v_add3_u32 v224, s34, v183, v128
	ds_read_b128 v[212:215], v224 offset:0
	ds_read_b128 v[216:219], v224 offset:32
	ds_read_b128 v[220:223], v224 offset:64
	v_mfma_f32_32x32x16_bf16 v[64:79], v[240:243], v[244:247], 0
	v_mfma_f32_32x32x16_bf16 v[80:95], v[240:243], v[248:251], 0
	s_waitcnt lgkmcnt(2)
	v_mfma_f32_32x32x16_bf16 v[64:79], v[212:215], v[130:133], v[64:79]
	v_mfma_f32_32x32x16_bf16 v[80:95], v[212:215], v[138:141], v[80:95]
	ds_read_b128 v[212:215], v224 offset:96
	s_waitcnt lgkmcnt(2)
	v_mfma_f32_32x32x16_bf16 v[64:79], v[216:219], v[134:137], v[64:79]
	v_mfma_f32_32x32x16_bf16 v[80:95], v[216:219], v[142:145], v[80:95]
	ds_read_b128 v[216:219], v224 offset:128
	s_waitcnt lgkmcnt(2)
	v_mfma_f32_32x32x16_bf16 v[64:79], v[220:223], v[146:149], v[64:79]
	v_mfma_f32_32x32x16_bf16 v[80:95], v[220:223], v[154:157], v[80:95]
	ds_read_b128 v[220:223], v224 offset:160
	s_waitcnt lgkmcnt(2)
	v_mfma_f32_32x32x16_bf16 v[64:79], v[212:215], v[150:153], v[64:79]
	v_mfma_f32_32x32x16_bf16 v[80:95], v[212:215], v[158:161], v[80:95]
	s_waitcnt lgkmcnt(1)
	v_mfma_f32_32x32x16_bf16 v[64:79], v[216:219], v[162:165], v[64:79]
	v_mfma_f32_32x32x16_bf16 v[80:95], v[216:219], v[170:173], v[80:95]
	s_waitcnt lgkmcnt(0)
	v_mfma_f32_32x32x16_bf16 v[64:79], v[220:223], v[166:169], v[64:79]
	v_mfma_f32_32x32x16_bf16 v[80:95], v[220:223], v[174:177], v[80:95]
	v_add3_u32 v225, s34, v187, v128
	ds_read_b128 v[196:199], v225 offset:13376
	ds_read_b128 v[200:203], v225 offset:17984
	ds_read_b128 v[204:207], v225 offset:13408
	ds_read_b128 v[208:211], v225 offset:18016
	s_nop 7
	s_nop 3
	s_nop 0
	s_nop 0
.Lat_loop:
	v_add3_u32 v224, s34, v183, v128
	ds_read_b128 v[212:215], v224 offset:6656
	ds_read_b128 v[216:219], v224 offset:6688
	ds_read_b128 v[220:223], v224 offset:6720
	s_waitcnt lgkmcnt(6)
	v_mfma_f32_32x32x16_bf16 v[16:31], v[196:199], v[96:99], v[16:31]
	v_max3_f32 v226, v64, v65, v66
	v_max3_f32 v236, v80, v81, v82
	v_max3_f32 v227, v67, v68, v69
	v_max3_f32 v237, v83, v84, v85
	s_waitcnt lgkmcnt(5)
	v_mfma_f32_32x32x16_bf16 v[48:63], v[200:203], v[96:99], v[48:63]
	v_max3_f32 v226, v226, v70, v71
	v_max3_f32 v236, v236, v86, v87
	v_max3_f32 v227, v227, v72, v73
	v_max3_f32 v237, v237, v88, v89
	s_waitcnt lgkmcnt(4)
	v_mfma_f32_32x32x16_bf16 v[16:31], v[204:207], v[100:103], v[16:31]
	v_max3_f32 v226, v226, v74, v75
	v_max3_f32 v236, v236, v90, v91
	v_max3_f32 v227, v227, v76, v77
	v_max3_f32 v237, v237, v92, v93
	s_waitcnt lgkmcnt(3)
	v_mfma_f32_32x32x16_bf16 v[48:63], v[208:211], v[100:103], v[48:63]
	v_max3_f32 v226, v226, v78, v79
	v_max3_f32 v236, v236, v94, v95
	v_max_f32_e32 v226, v226, v227
	v_max_f32_e32 v236, v236, v237
	v_cmp_lt_f32_e32 vcc, s33, v226
	s_cbranch_vccnz .Lat_resc_aE
